# v37: v25 with GEMM K-loop priority toggling replaced by one static priority raise per GEMM phase for waves 0-3
# speedup vs baseline: 1.0039x; 1.0039x over previous
.Lxb1_done:
.LBB0_391:
	s_or_b64 exec, exec, s[2:3]
	s_waitcnt lgkmcnt(0)
	s_barrier
	s_cmp_lt_u32 s68, 4
	s_cbranch_scc0 .Lprio2
	s_setprio 1
